# att-phase extras 2/4 with scan WGs 2
# speedup vs baseline: 1.0106x; 1.0061x over previous
; __global__ void __launch_bounds__(NWAVES * 64, 2) mega_fwd(Args A) {
;     ...
;     float* X = (float*)(ws + WS_X); bf16* H = (bf16*)(ws + WS_H); bf16* ACT = (bf16*)(ws + WS_ACT); bf16* PROJ = (bf16*)(ws + WS_PROJ);
;     bf16* Y = (bf16*)(ws + WS_Y); float* MACC = (float*)(ws + WS_MACC); bf16* MB = (bf16*)(ws + WS_MB); float* GO = (float*)(ws + WS_GO);
;     const float* COS = (const float*)(ws + WS_ROPE); const float* SIN = COS + (size_t)NTOK * 32;
;     { int t_ = threadIdx.x; asm volatile("" : "+v"(t_)); const int w_ = __builtin_amdgcn_readfirstlane(t_ >> 6); p0_prologue(A, lds, bx * NWAVES + w_, G * NWAVES, w_, t_ & 63); }
;     conv_until(A, lds, TL_WO1, 0);
;     xcd_barrier(bar);
; #pragma unroll 1
;     for (int step = 0; step < 3 * DEPTH; ++step) {
;         const int l = step / 3, kind = step - 3 * l;
;         unsigned char* wl = ws + WS_W + (size_t)l * LW_END;
;         const unsigned long long* ssq = (const unsigned long long*)(ws + WS_CTL + CTL_SSQ) + (size_t)step * NTOK; unsigned long long* ssq_next = (unsigned long long*)(ws + WS_CTL + CTL_SSQ) + (size_t)(step + 1) * NTOK;
;         if (kind != 1) {
;             { pg8::Gemm g{H, (const bf16*)(wl + (kind == 0 ? LW_WI1 : LW_WI2)), NTOK, NWI, DM}; pg8::StaticOrder S; S.init(NTOK, NWI, G, bx);
;               pg8::EpiSwiglu E{ACT, DFF, ssq};
;               pg8::gemm_phase<pg8::EpiSwiglu, pg8::StaticOrder, true, true>(lds + RING_OFF, g, S, E); }
;             { const int rem1 = ((NTOK / 256) * (NWI / 256)) % G;
;               conv_until(A, lds, l * TL_LAYER + (kind == 0 ? TL_WIN : TL_LAYER), (rem1 != 0 && bx >= rem1) ? 3 : 0); }
;             xcd_barrier(bar);
;         } else {
;             const bool std256 = (G == 256);
;             unsigned char* XB8 = ws + WS_X;
; #pragma unroll 1
;             for (int part = 0; part < 3; ++part) {
;                 bool do16, do8; int i16, n16, g8, c8, i8, n8;
;                 if (std256) { do16 = part == 0 || (part == 1 && bx < 64); i16 = part ? 2 : 0; n16 = part ? 1 : 2;
;                               do8 = (part == 1 && bx >= 64) || (part == 2 && bx < 128); g8 = part == 1 ? 192 : 128; c8 = part == 1 ? bx - 64 : bx; i8 = part == 1 ? 0 : 3; n8 = part == 1 ? 2 : 3; }
;                 else { do16 = part == 0; i16 = 0; n16 = 1 << 20; do8 = part == 1; g8 = G; c8 = bx; i8 = 0; n8 = 1 << 20; }
.LBB0_284:
	v_writelane_b32 v252, s64, 42
	s_nop 1
	v_writelane_b32 v252, s65, 43
	v_writelane_b32 v252, s66, 44
	v_writelane_b32 v252, s67, 45
	v_writelane_b32 v252, s68, 46
	v_writelane_b32 v252, s69, 47
	v_writelane_b32 v252, s70, 48
	v_writelane_b32 v252, s71, 49
	v_writelane_b32 v252, s72, 50
	v_writelane_b32 v252, s73, 51
	v_writelane_b32 v252, s74, 52
	v_writelane_b32 v252, s75, 53
	v_writelane_b32 v252, s76, 54
	v_writelane_b32 v252, s77, 55
	v_writelane_b32 v252, s78, 56
	v_writelane_b32 v252, s79, 57
	s_or_b64 exec, exec, s[0:1]
	s_cmpk_lg_i32 s95, 0x100
	s_cselect_b64 s[0:1], -1, 0
	s_and_b64 s[0:1], s[0:1], exec
	s_cselect_b32 s69, s95, 0x80
	s_add_i32 s4, s97, 0xffffff80
	s_cmpk_lg_i32 s95, 0x100
	s_cselect_b64 s[0:1], -1, 0
	s_and_b64 s[2:3], s[0:1], exec
	s_cselect_b32 s20, s97, s4
	v_readlane_b32 s4, v252, 2
	v_readlane_b32 s18, v252, 16
	v_readlane_b32 s19, v252, 17
	s_add_u32 s74, s18, 0x10000
	s_addc_u32 s2, s19, 0
	v_readlane_b32 s5, v252, 3
	v_readlane_b32 s6, v252, 4
	v_readlane_b32 s7, v252, 5
	v_readlane_b32 s8, v252, 6
	v_readlane_b32 s9, v252, 7
	v_readlane_b32 s10, v252, 8
	v_readlane_b32 s11, v252, 9
	v_readlane_b32 s12, v252, 10
	v_readlane_b32 s13, v252, 11
	v_readlane_b32 s14, v252, 12
	v_readlane_b32 s15, v252, 13
	v_readlane_b32 s16, v252, 14
	v_readlane_b32 s17, v252, 15
	v_writelane_b32 v252, s2, 58
	s_add_u32 s2, s18, 0x35e00000
	s_addc_u32 s3, s19, 0
	s_add_u32 s88, s18, 0x3b600000
	s_addc_u32 s89, s19, 0
	v_writelane_b32 v252, s2, 59
	s_add_u32 s12, s18, 0x45e00000
	s_addc_u32 s13, s19, 0
	v_writelane_b32 v252, s3, 60
	v_writelane_b32 v252, s12, 61
	s_add_u32 s2, s18, 0x4c200000
	v_writelane_b32 v252, s13, 62
	s_addc_u32 s3, s19, 0
	v_writelane_b32 v252, s2, 63
	s_waitcnt vmcnt(15)
	v_mov_b32_e32 v3, 0
	v_mov_b32_e32 v216, 1
	v_writelane_b32 v253, s3, 0
	s_add_u32 s2, s18, 0x4e200000
	s_addc_u32 s3, s19, 0
	v_writelane_b32 v253, s2, 1
	v_mov_b32_e32 v217, 0x7f7f7f7f
	v_mov_b32_e32 v225, 0x43e00000
	v_writelane_b32 v253, s3, 2
	s_add_u32 s2, s18, 0x4fa00000
	s_addc_u32 s3, s19, 0
	v_writelane_b32 v253, s2, 3
	v_mov_b64_e32 v[226:227], 0x2ff
	v_mov_b32_e32 v222, 0x41b17218
	v_writelane_b32 v253, s3, 4
	s_add_u32 s2, s18, 0x4fb00000
	s_addc_u32 s3, s19, 0
	v_writelane_b32 v253, s2, 5
	v_mbcnt_hi_u32_b32 v223, -1, v76
	v_mov_b32_e32 v224, 0xf149f2ca
	v_writelane_b32 v253, s3, 6
	s_add_u32 s2, s18, 0x200000
	v_writelane_b32 v253, s2, 7
	s_addc_u32 s2, s19, 0
	s_cmpk_lt_i32 s97, 0x580
	v_writelane_b32 v253, s2, 8
	s_cselect_b64 s[2:3], -1, 0
	v_writelane_b32 v253, s2, 9
	s_ashr_i32 s21, s97, 31
	s_movk_i32 s75, 0xc0
	v_writelane_b32 v253, s3, 10
	s_lshr_b32 s2, s21, 29
	s_add_i32 s3, s97, s2
	s_ashr_i32 s2, s3, 3
	s_and_b32 s3, s3, -8
	s_sub_i32 s5, s97, s3
	s_ashr_i32 s3, s95, 31
	s_add_u32 s6, s18, 0x4200
	v_writelane_b32 v253, s3, 11
	s_addc_u32 s7, s19, 0
	v_writelane_b32 v253, s6, 12
	s_movk_i32 s76, 0x300
	s_movk_i32 s77, 0x5400
	v_writelane_b32 v253, s7, 13
	s_add_u32 s6, s18, 0x4400
	s_addc_u32 s7, s19, 0
	v_writelane_b32 v253, s6, 14
	s_movk_i32 s81, 0x7fff
	s_mov_b32 s82, 0xffff0000
	v_writelane_b32 v253, s7, 15
	s_add_u32 s6, s18, 0x4500
	s_addc_u32 s7, s19, 0
	v_writelane_b32 v253, s6, 16
	s_movk_i32 s61, 0x1110
	s_movk_i32 s84, 0x15ff
	v_writelane_b32 v253, s7, 17
	s_add_u32 s6, s18, 0x4600
	s_addc_u32 s7, s19, 0
	v_writelane_b32 v253, s6, 18
	s_mov_b32 s85, 0xc3e00000
	s_movk_i32 s33, 0xff
	v_writelane_b32 v253, s7, 19
	s_add_u32 s6, s18, 0x4700
	s_addc_u32 s7, s19, 0
	v_writelane_b32 v253, s6, 20
	s_movk_i32 s66, 0x90
	s_mov_b32 s96, 0x2aaaaaab
	v_writelane_b32 v253, s7, 21
	s_add_u32 s6, s18, 0x4800
	s_addc_u32 s7, s19, 0
	v_writelane_b32 v253, s6, 22
	s_movk_i32 s36, 0x190
	s_movk_i32 s37, 0xff40
	v_writelane_b32 v253, s7, 23
	s_add_u32 s6, s18, 0x4900
	s_addc_u32 s7, s19, 0
	v_writelane_b32 v253, s6, 24
	s_movk_i32 s38, 0x567
	s_movk_i32 s39, 0x1500
	v_writelane_b32 v253, s7, 25
	s_add_u32 s6, s18, 0x4a00
	s_addc_u32 s7, s19, 0
	v_writelane_b32 v253, s6, 26
	s_movk_i32 s56, 0x1800
	s_movk_i32 s57, 0xc80
	v_writelane_b32 v253, s7, 27
	s_add_u32 s6, s18, 0x4b00
	s_addc_u32 s7, s19, 0
	v_writelane_b32 v253, s6, 28
	s_movk_i32 s58, 0x3ff
	s_mov_b32 s80, 0xefa18f08
	v_writelane_b32 v253, s7, 29
	s_add_u32 s6, s18, 0x4c00
	s_addc_u32 s7, s19, 0
	v_writelane_b32 v253, s6, 30
	s_mov_b32 s62, 0
	s_mov_b32 s94, 0x3e000000
	v_writelane_b32 v253, s7, 31
	s_add_u32 s6, s18, 0x4d00
	s_addc_u32 s7, s19, 0
	v_writelane_b32 v253, s6, 32
	s_waitcnt lgkmcnt(0)
	s_barrier
; __global__ void __launch_bounds__(NWAVES * 64, 2) mega_fwd(Args A) {
;     ...
;                 if (std256) { do16 = part == 0 || (part == 1 && bx < 64); i16 = part ? 2 : 0; n16 = part ? 1 : 2;
;                               do8 = (part == 1 && bx >= 64) || (part == 2 && bx < 128); g8 = part == 1 ? 192 : 128; c8 = part == 1 ? bx - 64 : bx; i8 = part == 1 ? 0 : 3; n8 = part == 1 ? 2 : 3; }
;                 else { do16 = part == 0; i16 = 0; n16 = 1 << 20; do8 = part == 1; g8 = G; c8 = bx; i8 = 0; n8 = 1 << 20; }
;                 if (do16) { pg8::Gemm g{H, (const bf16*)(wl + LW_WIN), NTOK, C_GATE, DM}; pg8::RangeOrder S; S.init(NTOK, C_GATE, G, bx); S.i0 = i16; S.n = n16;
;                     pg8::EpiProj E{PROJ, NPROJ, (const float*)A.in[7] + (size_t)l * 6144, 1 << 20, ssq, 1.0f};
;                     pg8::gemm_phase<pg8::EpiProj, pg8::RangeOrder, true, true>(lds + RING_OFF, g, S, E); }
;                 if (do8) { pg8::Gemm g{(const bf16*)XB8, (const bf16*)(wl + LW_WIN + WIN8_OFF), NTOK, 6144, DM / 2}; pg8::RangeOrder S; S.init(NTOK, 6144, g8, c8); S.i0 = i8; S.n = n8;
;                     pg8::EpiGate8 E{(unsigned char*)(PROJ + C_GATE), NPROJ * 2, (const float*)A.in[7] + (size_t)l * 6144, ssq, 1.0f / 2048.0f};
;                     pg8::gemm_phase<pg8::EpiGate8, pg8::RangeOrder, true, true, true>(lds + RING_OFF, g, S, E); }
;                 if (part == 1) xcd_barrier(bar);
;                 if (part == 2 && (!std256 || bx >= 128)) { const int mb = std256 ? bx - 128 : bx, ms = std256 ? 128 : G;
;                     if ((ms & 3) == 0) pool_units(lds, PROJ, (const bf16*)(ws + WS_WPT) + (size_t)l * 4 * 192 * 192, Y + (size_t)NTOK * BRW, mb, ms, 512);
;                     else for (int u = mb; u < 512; u += ms) pool_units(lds, PROJ, (const bf16*)(ws + WS_WPT) + (size_t)l * 4 * 192 * 192, Y + (size_t)NTOK * BRW, u, 512, 512);
;                     gla_pre_items(lds, PROJ, (const float*)A.in[11] + (size_t)l * 16 * 384, (const float*)A.in[12] + l * 384, ws + WS_GPRE, mb, ms, 512); }
;             }
;             xcd_barrier(bar);
;             if (G > 96) { if (bx < 48) gla_scan_unit(lds, ws + WS_GPRE, GO, bx);
;                           else for (int u = bx - 48; u < 256; u += G - 48) att_unit(lds, PROJ, COS, SIN, (const float*)A.in[8] + l * 12, Y, u); }
;             else { for (int u = bx; u < 48; u += G) gla_scan_unit(lds, ws + WS_GPRE, GO, u);
	v_writelane_b32 v253, s7, 33
	s_add_u32 s6, s18, 0x4e00
	s_addc_u32 s7, s19, 0
	v_writelane_b32 v253, s6, 34
	s_nop 1
	v_writelane_b32 v253, s7, 35
	s_add_u32 s6, s18, 0x4f00
	s_addc_u32 s7, s19, 0
	v_writelane_b32 v253, s6, 36
	s_nop 1
	v_writelane_b32 v253, s7, 37
	s_add_u32 s6, s18, 0x5000
	s_addc_u32 s7, s19, 0
	v_writelane_b32 v253, s6, 38
	s_nop 1
	v_writelane_b32 v253, s7, 39
	s_add_u32 s6, s18, 0x5100
	s_addc_u32 s7, s19, 0
	v_writelane_b32 v253, s6, 40
	s_nop 1
	v_writelane_b32 v253, s7, 41
	s_add_u32 s6, s18, 0x5200
	s_addc_u32 s7, s19, 0
	v_writelane_b32 v253, s6, 42
	s_nop 1
	v_writelane_b32 v253, s7, 43
	s_add_u32 s6, s18, 0x5300
	s_addc_u32 s7, s19, 0
	v_writelane_b32 v253, s6, 44
	s_nop 1
	v_writelane_b32 v253, s7, 45
	s_add_u32 s6, s18, 0x7400
	s_addc_u32 s7, s19, 0
	v_writelane_b32 v253, s6, 46
	s_nop 1
	v_writelane_b32 v253, s7, 47
	s_add_u32 s6, s18, 0x7500
	s_addc_u32 s7, s19, 0
	v_writelane_b32 v253, s6, 48
	s_cmpk_eq_i32 s95, 0x100
	s_nop 0
	v_writelane_b32 v253, s7, 49
	s_cselect_b64 s[6:7], -1, 0
	s_add_u32 s72, s18, 0x2fe00000
	s_addc_u32 s73, s19, 0
	v_writelane_b32 v253, s6, 50
	s_cmp_lt_i32 s97, 64
	s_nop 0
	v_writelane_b32 v253, s7, 51
	s_cselect_b64 s[6:7], -1, 0
	v_writelane_b32 v253, s6, 52
	s_cmp_gt_i32 s97, 63
	s_nop 0
	v_writelane_b32 v253, s7, 53
	s_cselect_b64 s[6:7], -1, 0
	v_writelane_b32 v253, s6, 54
	s_cmpk_lt_i32 s97, 0x80
	s_nop 0
	v_writelane_b32 v253, s7, 55
	s_cselect_b64 s[6:7], -1, 0
	v_writelane_b32 v253, s6, 56
	s_sub_i32 s3, s97, 64
	s_nop 0
	v_writelane_b32 v253, s7, 57
	s_add_u32 s6, s18, 0x3b602400
	v_writelane_b32 v253, s3, 58
	s_addc_u32 s7, s19, 0
	v_writelane_b32 v253, s6, 59
	s_cmpk_gt_i32 s97, 0x7f
	s_nop 0
	v_writelane_b32 v253, s7, 60
	s_cselect_b64 s[6:7], -1, 0
	s_or_b64 s[0:1], s[6:7], s[0:1]
	v_writelane_b32 v253, s0, 61
	s_nop 1
	v_writelane_b32 v253, s1, 62
	s_and_b32 s0, s69, 3
	s_cmp_lg_u32 s0, 0
	s_cselect_b64 s[0:1], -1, 0
	v_writelane_b32 v253, s0, 63
	s_cmpk_lt_i32 s20, 0x200
	s_nop 0
	v_writelane_b32 v254, s1, 0
	s_cselect_b64 s[0:1], -1, 0
	v_writelane_b32 v254, s0, 1
	s_nop 1
	v_writelane_b32 v254, s1, 2
	s_add_u32 s0, s18, 0x46a00000
	s_addc_u32 s1, s19, 0
	v_writelane_b32 v254, s0, 3
	s_and_b32 s4, s20, 3
	s_nop 0
	v_writelane_b32 v254, s1, 4
	s_mul_i32 s0, s4, 0x12000
	s_add_u32 s0, s34, s0
	v_writelane_b32 v254, s0, 5
	v_writelane_b32 v254, s34, 6
	s_addc_u32 s0, s35, 0
	s_lshl_b32 s68, 2, s4
	v_writelane_b32 v254, s35, 7
	v_writelane_b32 v254, s0, 8
	s_lshl_b32 s1, s20, 4
	s_lshl_b32 s0, s69, 4
	s_add_u32 s22, s18, 0x4fc00000
	v_writelane_b32 v254, s0, 9
	s_addc_u32 s23, s19, 0
	s_lshl_b32 s0, s20, 6
	s_and_b32 s0, s0, 0x7c0
	v_writelane_b32 v254, s1, 10
	s_and_b32 s1, s1, 0xfffff800
	s_or_b32 s0, s1, s0
	s_ashr_i32 s1, s0, 31
	v_writelane_b32 v254, s0, 11
	s_bfe_u32 s3, s20, 0x20005
	s_mov_b32 s35, 0
	v_writelane_b32 v254, s1, 12
	s_mul_i32 s0, s3, 0x60
	v_writelane_b32 v254, s20, 13
	s_add_i32 s1, s0, 0x920
	v_writelane_b32 v254, s1, 14
	v_writelane_b32 v254, s0, 15
	s_bitset1_b32 s0, 11
	s_cmpk_lt_i32 s95, 0x61
	v_writelane_b32 v254, s0, 16
	s_cselect_b64 s[0:1], -1, 0
	s_cmpk_gt_i32 s95, 0x60
	v_writelane_b32 v254, s0, 17
	s_cselect_b64 s[6:7], -1, 0
	s_cmp_lt_i32 s97, 48
	v_writelane_b32 v254, s1, 18
	s_cselect_b64 s[0:1], -1, 0
	v_writelane_b32 v254, s0, 19
	s_cmpk_lt_i32 s97, 0x100
	s_nop 0
	v_writelane_b32 v254, s1, 20
	s_cselect_b64 s[0:1], -1, 0
	v_writelane_b32 v254, s0, 21
	s_nop 1
	v_writelane_b32 v254, s1, 22
	s_sub_i32 s0, s97, 48
	v_writelane_b32 v254, s0, 23
	s_cmpk_lt_i32 s97, 0x130
	s_mul_hi_i32 s0, s97, 0x55555556
	s_cselect_b64 s[8:9], -1, 0
	s_lshr_b32 s1, s0, 31
	s_add_i32 s10, s0, s1
	s_mul_i32 s0, s10, -3
	s_add_i32 s0, s0, s97
	v_writelane_b32 v254, s8, 24
	s_lshl_b32 s1, s0, 13
	s_add_i32 s1, s1, 0x8000
	v_writelane_b32 v254, s9, 25
	v_writelane_b32 v254, s1, 26
	s_sub_i32 s1, s95, 48
	v_writelane_b32 v254, s1, 27
	s_lshl_b32 s8, s10, 5
	s_mul_i32 s1, s10, 0x1c4000
	v_writelane_b32 v254, s8, 28
	s_mul_hi_i32 s8, s8, 0xe200
	s_add_u32 s14, s22, s1
	s_addc_u32 s15, s23, s8
	s_add_u32 s8, s14, 0xe000
	v_writelane_b32 v254, s14, 29
	s_addc_u32 s9, s15, 0
	s_lshl_b32 s1, s10, 9
	s_lshl_b32 s0, s0, 6
	v_writelane_b32 v254, s15, 30
	s_and_b32 s11, s1, 0xfffff800
	s_ashr_i32 s1, s0, 31
	v_writelane_b32 v254, s8, 31
	s_cmp_gt_i32 s97, 47
	s_nop 0
	v_writelane_b32 v254, s9, 32
	s_cselect_b64 s[8:9], -1, 0
	v_writelane_b32 v254, s8, 33
	s_mov_b64 s[14:15], s[6:7]
	s_add_i32 s6, s97, s95
	s_addk_i32 s6, 0xffa0
	v_writelane_b32 v254, s9, 34
	s_cmpk_lt_i32 s6, 0x100
	s_cselect_b32 s8, 2, 4
	v_writelane_b32 v254, s14, 35
	s_and_b64 s[6:7], s[14:15], exec
	s_cselect_b32 s6, s8, 0
	v_writelane_b32 v254, s15, 36
	v_writelane_b32 v254, s6, 37
	s_add_u32 s6, s18, 0x47600000
	v_writelane_b32 v254, s6, 38
	s_addc_u32 s6, s19, 0
	v_writelane_b32 v254, s6, 39
	s_lshl_b32 s14, s95, 5
	s_lshl_b32 s6, s5, 5
	s_cmp_lt_i32 s5, 0
	s_movk_i32 s7, 0xb1
;     __host__ __device__ bool next(int i, Unit& u) const {
;         const long L = (long)i * G + c; if (L >= nwg) return false;
;         int wgid = (int)L; { const int q = nwg / NXCD, r = nwg % NXCD, xcd = wgid % NXCD, off = wgid / NXCD; wgid = (xcd < r ? xcd * (q + 1) : r * (q + 1) + (xcd - r) * q) + off; }
;         const int nig = WGM * nN, gid = wgid / nig, fm = gid * WGM, gsz = (nM - fm) < WGM ? (nM - fm) : WGM;
;         u.pm = fm + ((wgid % nig) % gsz); u.pn = (wgid % nig) / gsz; u.seg = 0; return true;
; __global__ void __launch_bounds__(NWAVES * 64, 2) mega_fwd(Args A) {
;     ...
;             { const int rem1 = ((NTOK / 256) * (NWI / 256)) % G;
;               conv_until(A, lds, l * TL_LAYER + (kind == 0 ? TL_WIN : TL_LAYER), (rem1 != 0 && bx >= rem1) ? 3 : 0); }
	s_cselect_b32 s7, s7, 0xb0
	s_mul_i32 s7, s5, s7
	s_mul_i32 s5, s5, 33
	s_cselect_b32 s5, s5, s6
	s_add_i32 s7, s7, s2
	s_mul_hi_i32 s6, s7, 0x2e8ba2e9
	s_lshr_b32 s8, s6, 31
	s_ashr_i32 s6, s6, 6
	s_add_i32 s6, s6, s8
	s_mul_i32 s8, s6, 0x160
	s_sub_i32 s7, s7, s8
	s_bfe_u32 s8, s7, 0x3001c
	s_add_i32 s8, s7, s8
	s_and_b32 s9, s8, 0xfff8
	s_sub_i32 s7, s7, s9
	s_lshl_b32 s6, s6, 3
	s_sext_i32_i16 s8, s8
	s_sext_i32_i16 s7, s7
	s_add_i32 s16, s6, s7
	s_ashr_i32 s6, s8, 3
	v_writelane_b32 v254, s6, 40
	s_lshr_b32 s6, s8, 3
	s_bfe_i64 s[6:7], s[6:7], 0x100000
	s_lshl_b64 s[6:7], s[6:7], 20
	v_writelane_b32 v254, s6, 41
	s_ashr_i32 s17, s16, 31
	s_nop 0
	v_writelane_b32 v254, s7, 42
	s_mov_b32 s6, s16
	v_writelane_b32 v254, s6, 43
	s_nop 1
	v_writelane_b32 v254, s7, 44
	s_lshl_b64 s[6:7], s[16:17], 20
	s_add_u32 s6, s90, s6
	s_addc_u32 s7, s91, s7
	s_add_u32 s8, s6, 0x80000
	s_addc_u32 s9, s7, 0
	v_writelane_b32 v254, s8, 45
	s_nop 1
	v_writelane_b32 v254, s9, 46
	s_add_u32 s8, s6, 0x2000
	v_writelane_b32 v254, s6, 47
	s_addc_u32 s9, s7, 0
	s_add_i32 s2, s5, s2
	s_ashr_i32 s5, s2, 31
	s_lshr_b32 s5, s5, 26
	s_add_i32 s5, s2, s5
	v_writelane_b32 v254, s7, 48
	s_and_b32 s6, s5, 0xffc0
	s_sub_i32 s2, s2, s6
	s_bfe_i32 s6, s2, 0x80000
	s_bfe_u32 s6, s6, 0x3000c
	s_add_i32 s6, s2, s6
	s_and_b32 s7, s6, 0xf8
	s_sub_i32 s2, s2, s7
	s_ashr_i32 s5, s5, 6
	s_lshl_b32 s5, s5, 3
	s_sext_i32_i8 s2, s2
	s_add_i32 s5, s5, s2
	s_bfe_i32 s2, s6, 0x80000
	v_writelane_b32 v254, s8, 49
	s_sext_i32_i16 s2, s2
	s_ashr_i32 s6, s2, 3
	v_writelane_b32 v254, s9, 50
	s_lshr_b32 s2, s2, 3
	v_writelane_b32 v254, s6, 51
	s_bfe_i64 s[6:7], s[2:3], 0x100000
	v_writelane_b32 v254, s6, 52
	s_mul_hi_i32 s2, s5, 0x60000
	s_nop 0
	v_writelane_b32 v254, s7, 53
	v_writelane_b32 v254, s5, 54
	s_mul_i32 s5, s5, 0x60000
	s_add_u32 s6, s12, s5
	s_addc_u32 s7, s13, s2
	s_add_u32 s8, s6, 0x30000
	s_addc_u32 s9, s7, 0
	v_writelane_b32 v254, s8, 55
	s_nop 1
	v_writelane_b32 v254, s9, 56
	s_add_u32 s8, s6, 0x2000
	v_writelane_b32 v254, s6, 57
	s_addc_u32 s9, s7, 0
	s_abs_i32 s2, s95
	v_cvt_f32_u32_e32 v1, s2
	v_writelane_b32 v254, s7, 58
	s_sub_i32 s5, 0, s2
	v_writelane_b32 v254, s8, 59
	v_rcp_iflag_f32_e32 v1, v1
	s_nop 0
	v_writelane_b32 v254, s9, 60
	v_mul_f32_e32 v1, 0x4f7ffffe, v1
	v_cvt_u32_f32_e32 v1, v1
	s_nop 0
	v_readfirstlane_b32 s6, v1
	s_mul_i32 s5, s5, s6
	s_mul_hi_u32 s5, s6, s5
	s_add_i32 s6, s6, s5
	s_mul_hi_u32 s5, s6, 0x580
	s_mul_i32 s5, s5, s2
	s_sub_i32 s5, 0x580, s5
	s_sub_i32 s6, s5, s2
	s_cmp_ge_u32 s5, s2
	s_cselect_b32 s5, s6, s5
	s_sub_i32 s6, s5, s2
	s_cmp_ge_u32 s5, s2
	s_cselect_b32 s2, s6, s5
	s_cmp_lg_u32 s2, 0
	s_cselect_b64 s[6:7], -1, 0
	s_cmp_ge_i32 s97, s2
	s_cselect_b64 s[8:9], -1, 0
	s_and_b64 s[6:7], s[6:7], s[8:9]
	s_mul_i32 s2, s4, 0xc0
	v_writelane_b32 v254, s6, 61
	s_and_b64 s[4:5], s[6:7], exec
	s_cselect_b32 s4, 3, 0
	v_writelane_b32 v254, s7, 62
	v_writelane_b32 v255, s2, 0
	s_lshl_b32 s2, s2, 1
	v_writelane_b32 v254, s4, 63
	s_add_u32 s4, s88, s2
	s_addc_u32 s5, s89, 0
	v_writelane_b32 v255, s4, 1
	s_and_b32 s2, s10, 3
	s_mulk_i32 s2, 0x300
	v_writelane_b32 v255, s5, 2
	s_mul_i32 s4, s11, 0xc00
	s_lshl_b32 s5, s97, 6
	s_or_b32 s2, s4, s2
	s_lshl_b64 s[0:1], s[0:1], 2
	v_writelane_b32 v255, s5, 3
	s_lshl_b32 s5, s95, 6
	s_mul_hi_i32 s4, s11, 0xc00
	s_add_u32 s0, s2, s0
	s_addc_u32 s1, s4, s1
	s_add_u32 s0, s18, s0
	v_writelane_b32 v255, s5, 4
	s_addc_u32 s1, s19, s1
	v_writelane_b32 v255, s0, 5
	s_mul_i32 s2, s95, 0x18000
	s_add_i32 s93, 0, 0x20180
	v_writelane_b32 v255, s1, 6
	s_mul_i32 s0, s3, 0xc0
	s_mul_hi_i32 s3, s14, 0xc00
	v_writelane_b32 v255, s2, 7
	s_lshl_b32 s1, s97, 9
	s_lshl_b32 s0, s0, 1
	v_writelane_b32 v255, s3, 8
	s_mul_i32 s2, s95, 0xa8000
	v_writelane_b32 v255, s14, 9
	s_mul_hi_i32 s3, s14, 0x5400
	v_writelane_b32 v255, s2, 10
	s_add_i32 s60, 0, 0x20184
	v_mov_b32_e32 v1, 0x358637bd
	v_writelane_b32 v255, s3, 11
	v_writelane_b32 v255, s1, 12
	s_lshl_b32 s1, s95, 11
	v_writelane_b32 v255, s1, 13
	s_lshl_b32 s1, s95, 4
	v_writelane_b32 v255, s1, 14
	s_lshl_b32 s1, s95, 10
	v_writelane_b32 v255, s1, 15
	s_lshl_b32 s1, s95, 9
	v_writelane_b32 v255, s1, 16
	s_add_i32 s1, 0, 0x20160
	v_writelane_b32 v255, s1, 17
	s_add_i32 s1, 0, 0x20164
	v_writelane_b32 v255, s1, 18
	s_add_i32 s1, 0, 0x2d00
	v_writelane_b32 v255, s1, 19
	v_writelane_b32 v255, s0, 20
	s_add_i32 s64, 0, 0x12600
	s_nop 0
	v_writelane_b32 v255, s1, 21
	s_add_i32 s0, 0, 0xf000
	v_writelane_b32 v255, s0, 22
	s_add_i32 s0, 0, 0x8800
	v_writelane_b32 v255, s0, 23
	v_writelane_b32 v255, s90, 24
	s_nop 1
	v_writelane_b32 v255, s91, 25
	v_writelane_b32 v255, s69, 26
	v_writelane_b32 v255, s88, 27
	s_nop 1
	v_writelane_b32 v255, s89, 28
	v_writelane_b32 v255, s21, 29
	v_writelane_b32 v255, s22, 30
	v_writelane_b32 v255, s23, 31
	v_writelane_b32 v255, s93, 32
	v_writelane_b32 v255, s60, 33
	v_writelane_b32 v255, s92, 34
	s_nop 1
	v_writelane_b32 v255, s93, 35
	s_branch .LBB0_287
